# phase 0: first token-row item's loads and pointer setup issued at phase start, overlapping the w_pool / dt-weight staging
# speedup vs baseline: 1.0266x; 1.0047x over previous
.LBB0_440:
	s_and_b64 vcc, exec, s[2:3]
	s_cbranch_vccz .LBB0_717
	s_cmp_eq_u32 s70, 0
	s_cbranch_scc0 .LBB0_717
	v_and_b32_e32 v158, 63, v174
	v_lshlrev_b32_e32 v158, 4, v158
	v_lshrrev_b32_e32 v168, 6, v174
	v_readlane_b32 s0, v255, 2
	v_lshlrev_b32_e32 v168, 2, v168
	s_lshl_b32 s0, s0, 5
	v_add_u32_e32 v168, s0, v168
	v_readlane_b32 s14, v254, 56
	v_readlane_b32 s15, v254, 57
	v_mov_b32_e32 v159, v26
	s_nop 1
	s_load_dwordx4 s[0:3], s[14:15], 0x0
	s_load_dwordx2 s[26:27], s[14:15], 0x10
	s_load_dwordx2 s[30:31], s[14:15], 0x48
	s_load_dwordx2 s[14:15], s[14:15], 0xa8
	s_waitcnt lgkmcnt(0)
	v_lshl_add_u64 v[248:249], s[0:1], 0, v[158:159]
	v_lshl_add_u64 v[250:251], s[2:3], 0, v[158:159]
	v_lshl_add_u64 v[252:253], s[26:27], 0, v[158:159]
	v_lshl_add_u64 v[226:227], s[30:31], 0, v[158:159]
	v_lshl_add_u64 v[170:171], s[14:15], 0, v[158:159]
	v_cmp_lt_i32_e64 s[2:3], s49, v168
	s_movk_i32 s26, 0x3fff
	v_cmp_lt_i32_e64 s[26:27], s26, v168
	v_add_u32_e32 v160, 0xffffc000, v168
	v_add_u32_e32 v161, 0xffffbe00, v168
	v_mov_b32_e32 v164, 0x1000
	v_cndmask_b32_e64 v162, v248, v250, s[26:27]
	v_cndmask_b32_e64 v163, v249, v251, s[26:27]
	v_cndmask_b32_e64 v160, v168, v160, s[26:27]
	v_cndmask_b32_e64 v162, v162, v252, s[2:3]
	v_cndmask_b32_e64 v163, v163, v253, s[2:3]
	v_cndmask_b32_e64 v160, v160, v161, s[2:3]
	v_mov_b32_e32 v166, 0x3000
	v_lshl_add_u32 v164, v160, 12, v164
	v_lshl_add_u32 v166, v160, 12, v166
	v_mov_b32_e32 v165, v26
	v_mov_b32_e32 v167, v26
	v_lshl_add_u64 v[164:165], v[162:163], 0, v[164:165]
	v_lshl_add_u64 v[166:167], v[162:163], 0, v[166:167]
	global_load_dwordx4 v[178:181], v[164:165], off offset:-4096 nt
	global_load_dwordx4 v[182:185], v[164:165], off offset:-3072 nt
	global_load_dwordx4 v[186:189], v[164:165], off offset:-2048 nt
	global_load_dwordx4 v[190:193], v[164:165], off offset:-1024 nt
	global_load_dwordx4 v[194:197], v[164:165], off nt
	global_load_dwordx4 v[198:201], v[164:165], off offset:1024 nt
	global_load_dwordx4 v[202:205], v[164:165], off offset:2048 nt
	global_load_dwordx4 v[206:209], v[164:165], off offset:3072 nt
	global_load_dwordx4 v[210:213], v[166:167], off offset:-4096 nt
	global_load_dwordx4 v[214:217], v[166:167], off offset:-3072 nt
	global_load_dwordx4 v[218:221], v[166:167], off offset:-2048 nt
	global_load_dwordx4 v[222:225], v[166:167], off offset:-1024 nt
	global_load_dwordx4 v[232:235], v[166:167], off nt
	global_load_dwordx4 v[236:239], v[166:167], off offset:1024 nt
	global_load_dwordx4 v[240:243], v[166:167], off offset:2048 nt
	global_load_dwordx4 v[244:247], v[166:167], off offset:3072 nt
	s_mov_b32 s0, 0xc600
	v_cmp_gt_i32_e32 vcc, s0, v176
	s_and_saveexec_b64 s[0:1], vcc
	v_readlane_b32 s6, v254, 60
	v_readlane_b32 s7, v254, 61
	s_cbranch_execz .LBB0_450
	v_cvt_f32_u32_e32 v1, s6
	v_readlane_b32 s2, v254, 56
	v_readlane_b32 s3, v254, 57
	s_load_dwordx2 s[2:3], s[2:3], 0x108
	v_rcp_iflag_f32_e32 v1, v1
	v_add_u32_e32 v177, s6, v176
	s_mov_b32 s4, 0xc600
	v_cmp_gt_i32_e32 vcc, s4, v177
	v_mul_f32_e32 v1, 0x4f7ffffe, v1
	v_cvt_u32_f32_e32 v1, v1
	s_waitcnt lgkmcnt(0)
	s_add_u32 s2, s2, 0x1bd0c000
	s_addc_u32 s3, s3, 0
	s_sub_i32 s4, 0, s6
	v_mul_lo_u32 v4, s4, v1
	v_max_i32_e32 v2, 0xc600, v177
	v_mul_hi_u32 v4, v1, v4
	v_cndmask_b32_e64 v3, 1, 2, vcc
	v_subb_co_u32_e32 v2, vcc, v2, v177, vcc
	v_add_u32_e32 v1, v1, v4
	v_mul_hi_u32 v1, v2, v1
	v_mul_lo_u32 v4, v1, s6
	v_sub_u32_e32 v2, v2, v4
	v_add_u32_e32 v4, 1, v1
	v_cmp_le_u32_e32 vcc, s6, v2
	s_nop 1
	v_cndmask_b32_e32 v1, v1, v4, vcc
	v_subrev_u32_e32 v4, s6, v2
	v_cndmask_b32_e32 v2, v2, v4, vcc
	v_add_u32_e32 v4, 1, v1
	v_cmp_le_u32_e32 vcc, s6, v2
	s_mov_b64 s[6:7], -1
	v_mov_b32_e32 v2, v176
	v_cndmask_b32_e32 v1, v1, v4, vcc
	v_add_u32_e32 v1, v3, v1
	v_cmp_lt_u32_e32 vcc, 1, v1
	s_and_saveexec_b64 s[4:5], vcc
	s_cbranch_execz .LBB0_447
	v_readlane_b32 s6, v254, 62
	v_and_b32_e32 v4, -2, v1
	v_readlane_b32 s7, v254, 63
	s_lshl_b32 s8, s6, 10
	s_mov_b32 s9, s8
	s_mov_b64 s[6:7], 0
	v_mov_b32_e32 v5, v4
	v_mov_b64_e32 v[2:3], v[176:177]

.LBB0_465:
	s_or_b64 exec, exec, s[0:1]
	v_readlane_b32 s0, v254, 56
	v_readlane_b32 s1, v254, 57
	s_waitcnt lgkmcnt(0)
	s_barrier
	s_load_dwordx2 s[18:19], s[0:1], 0x108
	v_readlane_b32 s0, v255, 2
	s_cmpk_gt_i32 s0, 0x24f
	v_ashrrev_i32_e32 v1, 4, v174
	v_readlane_b32 s1, v255, 3
	s_cbranch_scc1 .LBB0_506
	v_and_b32_e32 v2, 64, v230
	v_add_u32_e32 v2, 64, v2
	v_xor_b32_e32 v3, 1, v230
	v_cmp_lt_i32_e32 vcc, v3, v2
	v_and_b32_e32 v4, 63, v174
	v_readlane_b32 s0, v254, 56
	v_cndmask_b32_e32 v3, v230, v3, vcc
	v_lshlrev_b32_e32 v27, 2, v3
	v_xor_b32_e32 v3, 2, v230
	v_cmp_lt_i32_e32 vcc, v3, v2
	v_readlane_b32 s1, v254, 57
	s_add_u32 s22, s0, 8
	v_cndmask_b32_e32 v3, v230, v3, vcc
	s_waitcnt vmcnt(0)
	v_lshlrev_b32_e32 v112, 2, v3
	v_xor_b32_e32 v3, 4, v230
	v_cmp_lt_i32_e32 vcc, v3, v2
	s_addc_u32 s23, s1, 0
	v_lshlrev_b32_e32 v68, 2, v4
	v_cndmask_b32_e32 v3, v230, v3, vcc
	v_lshlrev_b32_e32 v113, 2, v3
	v_xor_b32_e32 v3, 8, v230
	v_cmp_lt_i32_e32 vcc, v3, v2
	v_mov_b32_e32 v69, v26
	s_add_u32 s24, s0, 16
	v_cndmask_b32_e32 v3, v230, v3, vcc
	v_lshlrev_b32_e32 v114, 2, v3
	v_xor_b32_e32 v3, 16, v230
	v_cmp_lt_i32_e32 vcc, v3, v2
	v_readlane_b32 s0, v254, 11
	s_addc_u32 s25, s1, 0
	v_cndmask_b32_e32 v3, v230, v3, vcc
	v_lshlrev_b32_e32 v115, 2, v3
	v_xor_b32_e32 v3, 32, v230
	v_cmp_lt_i32_e32 vcc, v3, v2
	v_lshl_add_u32 v117, v4, 4, s0
	s_mov_b64 s[0:1], 0x5100000
	v_cndmask_b32_e32 v2, v230, v3, vcc
	v_lshlrev_b32_e32 v116, 2, v2
	v_lshlrev_b32_e32 v2, 3, v4
	v_mov_b32_e32 v3, v26
	s_waitcnt lgkmcnt(0)
	v_lshl_add_u64 v[70:71], s[18:19], 0, v[2:3]
	v_and_b32_e32 v3, 32, v174
	v_cmp_eq_u32_e32 vcc, 0, v3
	v_and_b32_e32 v3, 16, v174
	v_lshl_add_u64 v[4:5], s[18:19], 0, v[68:69]
	v_cmp_eq_u32_e64 s[4:5], 0, v3
	v_and_b32_e32 v3, 8, v174
	v_lshl_add_u64 v[72:73], v[4:5], 0, s[0:1]
	v_cmp_eq_u32_e64 s[6:7], 0, v3
	v_and_b32_e32 v3, 4, v174
	v_readlane_b32 s0, v255, 2
	v_cmp_eq_u32_e64 s[8:9], 0, v3
	v_and_b32_e32 v3, 2, v174
	v_readlane_b32 s1, v255, 3
	v_and_b32_e32 v6, -4, v1
	v_and_b32_e32 v2, 15, v174
	v_cmp_eq_u32_e64 s[10:11], 0, v3
	v_and_b32_e32 v3, 1, v174
	s_mov_b32 s2, s0
	v_readlane_b32 s0, v254, 62
	v_cmp_eq_u32_e64 s[12:13], 0, v3
	v_lshl_add_u32 v74, s2, 5, v6
	s_lshl_b32 s28, s0, 5
	v_lshlrev_b32_e32 v69, 2, v2
	s_mov_b32 s29, s2
	v_readlane_b32 s1, v254, 63
	s_mov_b32 s30, 0
	s_branch .LBB0_469
